# output-pass wave roles rebalanced: waves 2,3 (idle during the state chain) take the decay/prefix-sum half of stage A; wave 2 takes N, E1, E2/E3; waves 0,1 keep the state chain
# speedup vs baseline: 1.1337x; 1.0128x over previous
.LBB0_1102:
	s_cmpk_gt_i32 s81, 0x1ff
	s_mov_b64 s[8:9], -1
	s_cbranch_scc0 .LBB0_1220
	s_add_i32 s52, s81, 0xfffffe00
	s_lshr_b32 s40, s52, 9
	s_and_b32 s82, s81, 15
	v_readfirstlane_b32 s12, v176
	s_cmpk_lt_u32 s12, 0x80
	s_cselect_b64 s[8:9], -1, 0
	s_cmpk_gt_u32 s12, 0x7f
	s_cselect_b64 s[48:49], -1, 0
	s_bfe_u32 s13, s12, 0x10006
	s_and_b64 s[10:11], s[8:9], exec
	s_cselect_b32 s10, 0xf800000, s66
	s_add_u32 s50, s14, s10
	s_addc_u32 s51, s15, 0
	s_lshl_b64 s[10:11], s[40:41], 17
	s_add_u32 s10, s50, s10
	s_addc_u32 s11, s51, s11
	s_lshl_b32 s84, s13, 5
	s_lshl_b32 s83, s82, 6
	v_or_b32_e32 v0, s84, v135
	v_or_b32_e32 v0, s83, v0
	v_lshlrev_b32_e32 v0, 7, v0
	v_lshl_add_u64 v[2:3], s[10:11], 0, v[0:1]
	s_and_b64 s[10:11], s[8:9], exec
	s_cselect_b32 s10, 0xa0, s67
	v_mov_b32_e32 v141, v1
	s_add_u32 s10, s0, s10
	v_lshl_add_u64 v[2:3], v[2:3], 0, v[140:141]
	s_addc_u32 s11, s1, 0
	global_load_dwordx4 v[82:85], v[2:3], off
	global_load_dwordx4 v[86:89], v[2:3], off offset:32
	global_load_dwordx4 v[90:93], v[2:3], off offset:64
	global_load_dwordx4 v[94:97], v[2:3], off offset:96
	s_load_dwordx2 s[10:11], s[10:11], 0x0
	s_lshl_b32 s50, s40, 10
	s_or_b32 s50, s50, s83
	s_or_b32 s50, s84, s50
	v_or_b32_e32 v0, s50, v135
	s_waitcnt lgkmcnt(0)
	v_lshl_add_u64 v[2:3], v[0:1], 2, s[10:11]
	global_load_dword v157, v[2:3], off
	s_and_saveexec_b64 s[10:11], s[6:7]
	s_cbranch_execz .LBB0_1105
	v_or_b32_e32 v0, s83, v176
	v_lshlrev_b32_e32 v0, 2, v0
	global_load_dword v2, v0, s[16:17]
	global_load_dword v3, v0, s[18:19]
	s_nop 0
	global_load_dword v0, v0, s[28:29]
	s_waitcnt vmcnt(1)
	ds_write2st64_b32 v151, v2, v3 offset0:238 offset1:239
	s_waitcnt vmcnt(0)
	ds_write_b32 v137, v0 offset:61632
.LBB0_1105:
	s_or_b64 exec, exec, s[10:11]
	s_bfe_u32 s86, s81, 0x50004
	s_lshr_b32 s85, s12, 6
	s_lshl_b32 s87, s86, 8
	s_and_b64 s[10:11], s[8:9], exec
	s_cselect_b32 s10, 0xe200000, s68
	s_add_u32 s10, s14, s10
	s_addc_u32 s11, s15, 0
	s_lshl_b32 s50, s40, 7
	s_add_u32 s50, s10, s50
	s_addc_u32 s51, s11, 0
	s_cmpk_lt_u32 s52, 0x200
	s_cselect_b64 s[10:11], -1, 0
	s_and_b64 s[52:53], s[10:11], exec
	s_cselect_b32 s52, 0, 0xe0
	v_cndmask_b32_e64 v0, v149, v135, s[10:11]
	s_or_b32 s52, s52, s87
	v_or_b32_e32 v0, s52, v0
	v_lshlrev_b32_e32 v0, 8, v0
	v_lshl_add_u64 v[2:3], s[50:51], 0, v[0:1]
	v_cndmask_b32_e64 v0, v150, v148, s[10:11]
	v_add_u32_e32 v142, s52, v0
	v_lshl_add_u64 v[2:3], v[2:3], 0, v[140:141]
	v_ashrrev_i32_e32 v143, 31, v142
	v_or_b32_e32 v6, s83, v147
	global_load_dwordx4 v[110:113], v[2:3], off offset:96
	global_load_dwordx4 v[106:109], v[2:3], off offset:64
	global_load_dwordx4 v[102:105], v[2:3], off offset:32
	global_load_dwordx4 v[98:101], v[2:3], off
	v_lshlrev_b64 v[2:3], 11, v[142:143]
	v_lshl_add_u64 v[4:5], s[36:37], 0, v[2:3]
	v_lshlrev_b32_e32 v0, 1, v6
	v_lshl_add_u64 v[6:7], s[34:35], 0, v[2:3]
	v_lshl_add_u64 v[2:3], s[30:31], 0, v[2:3]
	v_lshl_add_u64 v[4:5], v[4:5], 0, v[0:1]
	v_lshl_add_u64 v[2:3], v[2:3], 0, v[0:1]
	v_lshl_add_u64 v[6:7], v[6:7], 0, v[0:1]
	global_load_dwordx4 v[118:121], v[4:5], off
	global_load_dwordx4 v[114:117], v[6:7], off
	global_load_dwordx4 v[122:125], v[2:3], off
	s_lshl_b32 s52, s82, 2
	s_add_u32 s52, s64, s52
	s_addc_u32 s53, s65, 0
	s_and_b64 s[54:55], s[8:9], exec
	s_cmp_eq_u32 s85, 1
	s_cselect_b32 s89, s69, 0x5300
	s_cmp_eq_u32 s85, 2
	s_cselect_b32 s89, s69, s89
	s_cmp_eq_u32 s13, 0
	s_cselect_b32 s90, s70, 0x7700
	s_cmp_eq_u32 s85, 0
	s_cselect_b32 s13, s71, 0xd9c0
	s_cmp_lg_u32 s85, 1
	s_cselect_b32 s91, s13, 0xc5c0
	s_cmp_lg_u32 s85, 2
	v_mov_b32_e32 v14, v1
	v_mov_b32_e32 v15, v1
	s_cselect_b64 s[54:55], -1, 0
	s_lshl_b32 s12, s83, 2
	v_mov_b32_e32 v0, v1
	v_mov_b32_e32 v2, v1
	v_mov_b32_e32 v3, v1
	v_mov_b32_e32 v4, v1
	v_mov_b32_e32 v5, v1
	v_mov_b32_e32 v6, v1
	v_mov_b32_e32 v7, v1
	v_mov_b32_e32 v8, v1
	v_mov_b32_e32 v9, v1
	v_mov_b32_e32 v10, v1
	v_mov_b32_e32 v11, v1
	v_mov_b32_e32 v12, v1
	v_mov_b32_e32 v13, v1
	v_mov_b64_e32 v[32:33], v[14:15]
	s_add_u32 s56, s62, s12
	v_mov_b64_e32 v[30:31], v[12:13]
	v_mov_b64_e32 v[28:29], v[10:11]
	v_mov_b64_e32 v[26:27], v[8:9]
	v_mov_b64_e32 v[24:25], v[6:7]
	v_mov_b64_e32 v[22:23], v[4:5]
	v_mov_b64_e32 v[20:21], v[2:3]
	v_mov_b64_e32 v[18:19], v[0:1]
	v_mov_b64_e32 v[16:17], v[14:15]
	s_mov_b32 s88, 0
	s_addc_u32 s57, s63, 0
	s_lshl_b32 s92, s84, 1
	s_mov_b32 s93, 32
	s_movk_i32 s94, 0xc0
	v_mov_b64_e32 v[14:15], v[12:13]
	v_mov_b64_e32 v[12:13], v[10:11]
	v_mov_b64_e32 v[10:11], v[8:9]
	v_mov_b64_e32 v[8:9], v[6:7]
	v_mov_b64_e32 v[6:7], v[4:5]
	v_mov_b64_e32 v[4:5], v[2:3]
	v_mov_b64_e32 v[2:3], v[0:1]
	s_branch .LBB0_1107

.LBB0_1109:
	v_or_b32_e32 v71, s84, v70
	s_mov_b64 s[12:13], -1
	s_andn2_b64 vcc, exec, s[8:9]
	s_nop 7
	v_add_f32_e32 v58, v157, v34
	v_mul_u32_u24_e32 v34, 0x410, v51
	v_add_f32_e32 v57, v157, v35
	v_add_f32_e32 v56, v157, v36
	v_add_f32_e32 v55, v157, v37
	v_add_f32_e32 v54, v157, v38
	v_add_f32_e32 v53, v157, v39
	v_add_f32_e32 v52, v157, v40
	v_add_f32_e32 v50, v157, v41
	v_add_f32_e32 v42, v157, v42
	v_add_f32_e32 v41, v157, v43
	v_add_f32_e32 v40, v157, v44
	v_add_f32_e32 v39, v157, v45
	v_add_f32_e32 v38, v157, v46
	v_add_f32_e32 v37, v157, v47
	v_add_f32_e32 v36, v157, v48
	v_add_f32_e32 v35, v157, v49
	s_cbranch_vccnz .LBB0_1111
	v_mul_f32_e32 v43, 0xbfb8aa3b, v58
	v_mul_f32_e32 v45, 0xbfb8aa3b, v57
	v_exp_f32_e32 v44, v43
	v_exp_f32_e32 v45, v45
	v_mul_f32_e32 v48, 0xbfb8aa3b, v56
	v_mul_f32_e32 v49, 0xbfb8aa3b, v55
	v_add_f32_e32 v44, 1.0, v44
	v_add_f32_e32 v45, 1.0, v45
	v_rcp_f32_e32 v44, v44
	v_rcp_f32_e32 v45, v45
	v_exp_f32_e32 v48, v48
	v_exp_f32_e32 v49, v49
	v_mul_u32_u24_e32 v43, 0x410, v51
	v_lshl_add_u32 v46, v71, 2, v43
	v_add_u32_e32 v47, 0x2000, v46
	ds_write2_b32 v47, v44, v45 offset0:32 offset1:97
	v_add_f32_e32 v44, 1.0, v48
	v_add_f32_e32 v45, 1.0, v49
	v_mul_f32_e32 v48, 0xbfb8aa3b, v54
	v_mul_f32_e32 v49, 0xbfb8aa3b, v53
	v_rcp_f32_e32 v44, v44
	v_rcp_f32_e32 v45, v45
	v_exp_f32_e32 v48, v48
	v_exp_f32_e32 v49, v49
	s_mov_b64 s[12:13], 0
	ds_write2_b32 v47, v44, v45 offset0:162 offset1:227
	v_add_f32_e32 v44, 1.0, v48
	v_add_f32_e32 v45, 1.0, v49
	v_mul_f32_e32 v48, 0xbfb8aa3b, v52
	v_mul_f32_e32 v49, 0xbfb8aa3b, v50
	v_rcp_f32_e32 v44, v44
	v_rcp_f32_e32 v45, v45
	v_exp_f32_e32 v48, v48
	v_exp_f32_e32 v49, v49
	v_add_u32_e32 v47, 0x2800, v46
	ds_write2_b32 v47, v44, v45 offset0:40 offset1:105
	v_add_f32_e32 v44, 1.0, v48
	v_add_f32_e32 v45, 1.0, v49
	v_mul_f32_e32 v48, 0xbfb8aa3b, v42
	v_mul_f32_e32 v49, 0xbfb8aa3b, v41
	v_rcp_f32_e32 v44, v44
	v_rcp_f32_e32 v45, v45
	v_exp_f32_e32 v48, v48
	v_exp_f32_e32 v49, v49
	ds_write2_b32 v47, v44, v45 offset0:170 offset1:235
	v_add_f32_e32 v44, 1.0, v48
	v_add_f32_e32 v45, 1.0, v49
	v_mul_f32_e32 v48, 0xbfb8aa3b, v40
	v_mul_f32_e32 v49, 0xbfb8aa3b, v39
	v_rcp_f32_e32 v44, v44
	v_rcp_f32_e32 v45, v45
	v_exp_f32_e32 v48, v48
	v_exp_f32_e32 v49, v49
	v_add_u32_e32 v47, 0x3000, v46
	ds_write2_b32 v47, v44, v45 offset0:48 offset1:113
	v_add_f32_e32 v44, 1.0, v48
	v_add_f32_e32 v45, 1.0, v49
	v_mul_f32_e32 v48, 0xbfb8aa3b, v38
	v_rcp_f32_e32 v44, v44
	v_rcp_f32_e32 v45, v45
	v_exp_f32_e32 v48, v48
	v_mul_f32_e32 v49, 0xbfb8aa3b, v37
	v_exp_f32_e32 v49, v49
	ds_write2_b32 v47, v44, v45 offset0:178 offset1:243
	v_add_f32_e32 v44, 1.0, v48
	v_rcp_f32_e32 v45, v44
	v_add_f32_e32 v44, 1.0, v49
	v_rcp_f32_e32 v47, v44
	v_mul_f32_e32 v44, 0xbfb8aa3b, v36
	v_exp_f32_e32 v44, v44
	v_mul_f32_e32 v48, 0xbfb8aa3b, v35
	v_exp_f32_e32 v48, v48
	v_add_u32_e32 v49, 0x3800, v46
	v_add_f32_e32 v44, 1.0, v44
	v_rcp_f32_e32 v59, v44
	v_add_f32_e32 v44, 1.0, v48
	v_rcp_f32_e32 v44, v44
	ds_write2_b32 v49, v45, v47 offset0:56 offset1:121
	ds_write_b32 v46, v59 offset:15080

.LBB0_1149:
	v_mul_u32_u24_e32 v34, 0x48, v70
	v_lshlrev_b32_e32 v66, 1, v34
	s_waitcnt lgkmcnt(0)
	s_barrier
	v_add3_u32 v50, s89, v66, v0
	ds_read_b128 v[34:37], v50
	v_add3_u32 v0, s90, v66, v0
	ds_read_b128 v[38:41], v0
	ds_read_b128 v[52:55], v50 offset:32
	ds_read_b128 v[56:59], v0 offset:32
	s_mov_b64 s[58:59], -1
	s_and_b64 vcc, exec, s[54:55]
	s_waitcnt lgkmcnt(2)
	v_mfma_f32_32x32x16_bf16 v[34:49], v[34:37], v[38:41], 0
	s_waitcnt lgkmcnt(0)
	v_mfma_f32_32x32x16_bf16 v[34:49], v[52:55], v[56:59], v[34:49]
	ds_read_b128 v[52:55], v50 offset:64
	ds_read_b128 v[56:59], v0 offset:64
	ds_read_b128 v[60:63], v50 offset:96
	ds_read_b128 v[72:75], v0 offset:96
	v_lshlrev_b32_e32 v0, 2, v51
	v_cmp_lt_u32_e64 s[12:13], v70, v0
	v_lshl_add_u32 v50, v70, 1, s91
	s_waitcnt lgkmcnt(2)
	v_mfma_f32_32x32x16_bf16 v[34:49], v[52:55], v[56:59], v[34:49]
	v_cndmask_b32_e64 v52, 0, 1, s[12:13]
	v_cmp_le_u32_e64 s[12:13], v70, v0
	s_nop 1
	v_cndmask_b32_e64 v53, 0, 1, s[12:13]
	v_cndmask_b32_e64 v52, v53, v52, s[8:9]
	v_and_b32_e32 v52, 1, v52
	s_waitcnt lgkmcnt(0)
	v_mfma_f32_32x32x16_bf16 v[34:49], v[60:63], v[72:75], v[34:49]
	v_or_b32_e32 v143, 1, v0
	v_or_b32_e32 v158, 2, v0
	v_or_b32_e32 v159, 3, v0
	v_or_b32_e32 v160, 8, v0
	v_or_b32_e32 v161, 9, v0
	v_or_b32_e32 v162, 10, v0
	v_or_b32_e32 v163, 11, v0
	v_or_b32_e32 v164, 16, v0
	v_or_b32_e32 v165, 17, v0
	v_or_b32_e32 v166, 18, v0
	v_or_b32_e32 v167, 19, v0
	v_or_b32_e32 v168, 24, v0
	v_or_b32_e32 v169, 25, v0
	v_or_b32_e32 v170, 26, v0
	v_or_b32_e32 v171, 27, v0
	s_cmp_eq_u64 s[54:55], 0
	s_cbranch_scc1 .Ld_w0_b
	s_cmp_lg_u32 s89, s69
	s_cbranch_scc1 .Ld_w23_b
	v_mul_u32_u24_e32 v52, 0x50, v0
	v_add_u32_e32 v52, v52, v50
	v_cmp_lt_u32_e32 vcc, v70, v0
	v_cmp_lt_u32_e64 s[12:13], v70, v143
	v_cmp_lt_u32_e64 s[58:59], v70, v158
	v_cndmask_b32_e64 v34, 0, v34, vcc
	v_cmp_lt_u32_e32 vcc, v70, v159
	v_cndmask_b32_e64 v35, 0, v35, s[12:13]
	v_cmp_lt_u32_e64 s[12:13], v70, v160
	v_cvt_pk_bf16_f32 v53, v34, v35
	ds_write_b16 v52, v53 offset:0
	ds_write_b16_d16_hi v52, v53 offset:80
	v_cndmask_b32_e64 v36, 0, v36, s[58:59]
	v_cmp_lt_u32_e64 s[58:59], v70, v161
	v_cndmask_b32_e64 v37, 0, v37, vcc
	v_cmp_lt_u32_e32 vcc, v70, v162
	v_cvt_pk_bf16_f32 v53, v36, v37
	ds_write_b16 v52, v53 offset:160
	ds_write_b16_d16_hi v52, v53 offset:240
	v_cndmask_b32_e64 v38, 0, v38, s[12:13]
	v_cmp_lt_u32_e64 s[12:13], v70, v163
	v_cndmask_b32_e64 v39, 0, v39, s[58:59]
	v_cmp_lt_u32_e64 s[58:59], v70, v164
	v_cvt_pk_bf16_f32 v53, v38, v39
	ds_write_b16 v52, v53 offset:640
	ds_write_b16_d16_hi v52, v53 offset:720
	v_cndmask_b32_e64 v40, 0, v40, vcc
	v_cmp_lt_u32_e32 vcc, v70, v165
	v_cndmask_b32_e64 v41, 0, v41, s[12:13]
	v_cmp_lt_u32_e64 s[12:13], v70, v166
	v_cvt_pk_bf16_f32 v53, v40, v41
	ds_write_b16 v52, v53 offset:800
	ds_write_b16_d16_hi v52, v53 offset:880
	v_cndmask_b32_e64 v42, 0, v42, s[58:59]
	v_cmp_lt_u32_e64 s[58:59], v70, v167
	v_cndmask_b32_e64 v43, 0, v43, vcc
	v_cmp_lt_u32_e32 vcc, v70, v168
	v_cvt_pk_bf16_f32 v53, v42, v43
	ds_write_b16 v52, v53 offset:1280
	ds_write_b16_d16_hi v52, v53 offset:1360
	v_cndmask_b32_e64 v44, 0, v44, s[12:13]
	v_cmp_lt_u32_e64 s[12:13], v70, v169
	v_cndmask_b32_e64 v45, 0, v45, s[58:59]
	v_cmp_lt_u32_e64 s[58:59], v70, v170
	v_cvt_pk_bf16_f32 v53, v44, v45
	ds_write_b16 v52, v53 offset:1440
	ds_write_b16_d16_hi v52, v53 offset:1520
	v_cndmask_b32_e64 v46, 0, v46, vcc
	v_cmp_lt_u32_e32 vcc, v70, v171
	v_cndmask_b32_e64 v47, 0, v47, s[12:13]
	v_cvt_pk_bf16_f32 v53, v46, v47
	ds_write_b16 v52, v53 offset:1920
	ds_write_b16_d16_hi v52, v53 offset:2000
	v_cndmask_b32_e64 v48, 0, v48, s[58:59]
	v_cndmask_b32_e64 v49, 0, v49, vcc
	v_cvt_pk_bf16_f32 v53, v48, v49
	ds_write_b16 v52, v53 offset:2080
	ds_write_b16_d16_hi v52, v53 offset:2160
	s_branch .Ld_done_b

.Ld_done_b:
.LBB0_1211:
	v_add_u32_e32 v35, 0xffffff80, v141
	v_cmp_gt_u32_e32 vcc, 32, v35
	v_and_b32_e32 v34, 15, v141
	s_and_saveexec_b64 s[58:59], vcc
	s_cbranch_execz .LBB0_1213
.LBB0_1212:
	v_bfe_u32 v67, v141, 4, 1
	v_mul_u32_u24_e32 v35, 0x880, v67
	v_add_u32_e32 v35, 0x2080, v35
	v_add_u32_e32 v50, 0x420, v35
	v_cmp_eq_u32_e32 vcc, 0, v34
	v_cmp_eq_u32_e64 s[12:13], 1, v34
	ds_read_b32 v52, v35 offset:4
	v_cndmask_b32_e64 v36, 0, 1.0, vcc
	ds_read2_b32 v[54:55], v35 offset0:2 offset1:3
	v_cmp_eq_u32_e32 vcc, 2, v34
	v_cndmask_b32_e64 v37, 0, 1.0, s[12:13]
	ds_read2_b32 v[56:57], v35 offset0:4 offset1:5
	v_cmp_eq_u32_e64 s[12:13], 3, v34
	v_cndmask_b32_e64 v38, 0, 1.0, vcc
	ds_read2_b32 v[58:59], v35 offset0:6 offset1:7
	v_cmp_eq_u32_e32 vcc, 4, v34
	v_cndmask_b32_e64 v39, 0, 1.0, s[12:13]
	ds_read2_b32 v[60:61], v35 offset0:8 offset1:9
	v_cmp_eq_u32_e64 s[12:13], 5, v34
	v_cndmask_b32_e64 v40, 0, 1.0, vcc
	ds_read2_b32 v[62:63], v35 offset0:10 offset1:11
	v_cmp_eq_u32_e32 vcc, 6, v34
	v_cndmask_b32_e64 v41, 0, 1.0, s[12:13]
	ds_read2_b32 v[64:65], v35 offset0:12 offset1:13
	v_cmp_eq_u32_e64 s[12:13], 7, v34
	v_cndmask_b32_e64 v42, 0, 1.0, vcc
	ds_read2_b32 v[72:73], v35 offset0:14 offset1:15
	v_cmp_eq_u32_e32 vcc, 8, v34
	v_cndmask_b32_e64 v43, 0, 1.0, s[12:13]
	ds_read2_b32 v[74:75], v35 offset0:35 offset1:36
	v_cmp_eq_u32_e64 s[12:13], 9, v34
	v_cndmask_b32_e64 v44, 0, 1.0, vcc
	ds_read2_b32 v[76:77], v35 offset0:37 offset1:38
	v_cmp_eq_u32_e32 vcc, 10, v34
	v_cndmask_b32_e64 v45, 0, 1.0, s[12:13]
	v_cmp_eq_u32_e64 s[12:13], 11, v34
	v_cndmask_b32_e64 v46, 0, 1.0, vcc
	v_cmp_eq_u32_e32 vcc, 12, v34
	v_cndmask_b32_e64 v47, 0, 1.0, s[12:13]
	v_cmp_eq_u32_e64 s[12:13], 13, v34
	v_cndmask_b32_e64 v48, 0, 1.0, vcc
	v_cmp_eq_u32_e32 vcc, 14, v34
	v_cndmask_b32_e64 v49, 0, 1.0, s[12:13]
	v_cmp_eq_u32_e64 s[12:13], 15, v34
	v_cndmask_b32_e64 v68, 0, 1.0, vcc
	s_nop 0
	v_cndmask_b32_e64 v69, 0, 1.0, s[12:13]
	s_waitcnt lgkmcnt(6)
	v_fmac_f32_e32 v37, v36, v52
	v_pk_fma_f32 v[38:39], v[36:37], v[54:55], v[38:39] op_sel:[0,0,0] op_sel_hi:[0,1,1]
	v_pk_fma_f32 v[40:41], v[36:37], v[56:57], v[40:41] op_sel:[0,0,0] op_sel_hi:[0,1,1]
	v_pk_fma_f32 v[42:43], v[36:37], v[58:59], v[42:43] op_sel:[0,0,0] op_sel_hi:[0,1,1]
	ds_read2_b32 v[52:53], v35 offset0:39 offset1:40
	ds_read2_b32 v[54:55], v35 offset0:41 offset1:42
	ds_read2_b32 v[56:57], v35 offset0:43 offset1:44
	ds_read2_b32 v[58:59], v35 offset0:45 offset1:46
	s_waitcnt lgkmcnt(6)
	v_pk_fma_f32 v[44:45], v[36:37], v[60:61], v[44:45] op_sel:[0,0,0] op_sel_hi:[0,1,1]
	v_pk_fma_f32 v[46:47], v[36:37], v[62:63], v[46:47] op_sel:[0,0,0] op_sel_hi:[0,1,1]
	v_pk_fma_f32 v[48:49], v[36:37], v[64:65], v[48:49] op_sel:[0,0,0] op_sel_hi:[0,1,1]
	v_pk_fma_f32 v[68:69], v[36:37], v[72:73], v[68:69] op_sel:[0,0,0] op_sel_hi:[0,1,1]
	ds_read2_b32 v[60:61], v35 offset0:47 offset1:48
	ds_read_b32 v62, v35 offset:276
	ds_read2_b32 v[64:65], v35 offset0:70 offset1:71
	ds_read2_b32 v[72:73], v35 offset0:72 offset1:73
	s_waitcnt lgkmcnt(6)
	v_pk_fma_f32 v[38:39], v[36:37], v[74:75], v[38:39] op_sel:[1,0,0] op_sel_hi:[1,1,1]
	v_pk_fma_f32 v[40:41], v[36:37], v[76:77], v[40:41] op_sel:[1,0,0] op_sel_hi:[1,1,1]
	v_pk_fma_f32 v[42:43], v[36:37], v[52:53], v[42:43] op_sel:[1,0,0] op_sel_hi:[1,1,1]
	v_pk_fma_f32 v[44:45], v[36:37], v[54:55], v[44:45] op_sel:[1,0,0] op_sel_hi:[1,1,1]
	ds_read2_b32 v[74:75], v35 offset0:74 offset1:75
	ds_read2_b32 v[76:77], v35 offset0:76 offset1:77
	ds_read2_b32 v[52:53], v35 offset0:78 offset1:79
	ds_read2_b32 v[54:55], v35 offset0:80 offset1:81
	s_waitcnt lgkmcnt(6)
	v_pk_fma_f32 v[46:47], v[36:37], v[56:57], v[46:47] op_sel:[1,0,0] op_sel_hi:[1,1,1]
	v_pk_fma_f32 v[48:49], v[36:37], v[58:59], v[48:49] op_sel:[1,0,0] op_sel_hi:[1,1,1]
	v_pk_fma_f32 v[68:69], v[36:37], v[60:61], v[68:69] op_sel:[1,0,0] op_sel_hi:[1,1,1]
	v_fmac_f32_e32 v39, v38, v62
	ds_read2_b32 v[56:57], v35 offset0:103 offset1:104
	ds_read2_b32 v[58:59], v35 offset0:105 offset1:106
	ds_read2_b32 v[60:61], v35 offset0:107 offset1:108
	ds_read2_b32 v[62:63], v35 offset0:109 offset1:110
	s_waitcnt lgkmcnt(6)
	v_pk_fma_f32 v[40:41], v[38:39], v[64:65], v[40:41] op_sel:[0,0,0] op_sel_hi:[0,1,1]
	v_pk_fma_f32 v[42:43], v[38:39], v[72:73], v[42:43] op_sel:[0,0,0] op_sel_hi:[0,1,1]
	v_pk_fma_f32 v[44:45], v[38:39], v[74:75], v[44:45] op_sel:[0,0,0] op_sel_hi:[0,1,1]
	v_pk_fma_f32 v[46:47], v[38:39], v[76:77], v[46:47] op_sel:[0,0,0] op_sel_hi:[0,1,1]
	ds_read2_b32 v[64:65], v35 offset0:111 offset1:112
	ds_read2_b32 v[72:73], v35 offset0:113 offset1:114
	ds_read_b32 v74, v35 offset:548
	ds_read2_b32 v[76:77], v35 offset0:138 offset1:139
	s_waitcnt lgkmcnt(6)
	v_pk_fma_f32 v[48:49], v[38:39], v[52:53], v[48:49] op_sel:[0,0,0] op_sel_hi:[0,1,1]
	v_pk_fma_f32 v[68:69], v[38:39], v[54:55], v[68:69] op_sel:[0,0,0] op_sel_hi:[0,1,1]
	v_pk_fma_f32 v[40:41], v[38:39], v[56:57], v[40:41] op_sel:[1,0,0] op_sel_hi:[1,1,1]
	v_pk_fma_f32 v[42:43], v[38:39], v[58:59], v[42:43] op_sel:[1,0,0] op_sel_hi:[1,1,1]
	ds_read2_b32 v[52:53], v35 offset0:140 offset1:141
	ds_read2_b32 v[54:55], v35 offset0:142 offset1:143
	ds_read2_b32 v[56:57], v35 offset0:144 offset1:145
	ds_read2_b32 v[58:59], v35 offset0:146 offset1:147
	s_waitcnt lgkmcnt(6)
	v_pk_fma_f32 v[44:45], v[38:39], v[60:61], v[44:45] op_sel:[1,0,0] op_sel_hi:[1,1,1]
	v_pk_fma_f32 v[46:47], v[38:39], v[62:63], v[46:47] op_sel:[1,0,0] op_sel_hi:[1,1,1]
	v_pk_fma_f32 v[48:49], v[38:39], v[64:65], v[48:49] op_sel:[1,0,0] op_sel_hi:[1,1,1]
	v_pk_fma_f32 v[68:69], v[38:39], v[72:73], v[68:69] op_sel:[1,0,0] op_sel_hi:[1,1,1]
	ds_read2_b32 v[60:61], v35 offset0:171 offset1:172
	ds_read2_b32 v[62:63], v35 offset0:173 offset1:174
	ds_read2_b32 v[64:65], v35 offset0:175 offset1:176
	ds_read2_b32 v[72:73], v35 offset0:177 offset1:178
	s_waitcnt lgkmcnt(6)
	v_fmac_f32_e32 v41, v40, v74
	v_pk_fma_f32 v[42:43], v[40:41], v[76:77], v[42:43] op_sel:[0,0,0] op_sel_hi:[0,1,1]
	v_pk_fma_f32 v[44:45], v[40:41], v[52:53], v[44:45] op_sel:[0,0,0] op_sel_hi:[0,1,1]
	v_pk_fma_f32 v[46:47], v[40:41], v[54:55], v[46:47] op_sel:[0,0,0] op_sel_hi:[0,1,1]
	ds_read2_b32 v[74:75], v35 offset0:179 offset1:180
	ds_read_b32 v76, v35 offset:820
	ds_read2_b32 v[52:53], v35 offset0:206 offset1:207
	ds_read2_b32 v[54:55], v35 offset0:208 offset1:209
	s_waitcnt lgkmcnt(6)
	v_pk_fma_f32 v[48:49], v[40:41], v[56:57], v[48:49] op_sel:[0,0,0] op_sel_hi:[0,1,1]
	v_pk_fma_f32 v[68:69], v[40:41], v[58:59], v[68:69] op_sel:[0,0,0] op_sel_hi:[0,1,1]
	v_pk_fma_f32 v[42:43], v[40:41], v[60:61], v[42:43] op_sel:[1,0,0] op_sel_hi:[1,1,1]
	v_pk_fma_f32 v[44:45], v[40:41], v[62:63], v[44:45] op_sel:[1,0,0] op_sel_hi:[1,1,1]
	ds_read2_b32 v[56:57], v35 offset0:210 offset1:211
	ds_read2_b32 v[58:59], v35 offset0:212 offset1:213
	ds_read2_b32 v[60:61], v35 offset0:239 offset1:240
	ds_read2_b32 v[62:63], v35 offset0:241 offset1:242
	s_waitcnt lgkmcnt(6)
	v_pk_fma_f32 v[46:47], v[40:41], v[64:65], v[46:47] op_sel:[1,0,0] op_sel_hi:[1,1,1]
	v_pk_fma_f32 v[48:49], v[40:41], v[72:73], v[48:49] op_sel:[1,0,0] op_sel_hi:[1,1,1]
	v_pk_fma_f32 v[68:69], v[40:41], v[74:75], v[68:69] op_sel:[1,0,0] op_sel_hi:[1,1,1]
	v_fmac_f32_e32 v43, v42, v76
	ds_read2_b32 v[64:65], v35 offset0:243 offset1:244
	ds_read2_b32 v[72:73], v35 offset0:245 offset1:246
	ds_read_b32 v74, v50 offset:36
	ds_read2_b32 v[76:77], v50 offset0:10 offset1:11
	s_waitcnt lgkmcnt(6)
	v_pk_fma_f32 v[44:45], v[42:43], v[52:53], v[44:45] op_sel:[0,0,0] op_sel_hi:[0,1,1]
	v_pk_fma_f32 v[46:47], v[42:43], v[54:55], v[46:47] op_sel:[0,0,0] op_sel_hi:[0,1,1]
	v_pk_fma_f32 v[48:49], v[42:43], v[56:57], v[48:49] op_sel:[0,0,0] op_sel_hi:[0,1,1]
	v_pk_fma_f32 v[68:69], v[42:43], v[58:59], v[68:69] op_sel:[0,0,0] op_sel_hi:[0,1,1]
	ds_read2_b32 v[52:53], v50 offset0:12 offset1:13
	ds_read2_b32 v[54:55], v50 offset0:14 offset1:15
	ds_read2_b32 v[56:57], v50 offset0:43 offset1:44
	ds_read2_b32 v[58:59], v50 offset0:45 offset1:46
	s_waitcnt lgkmcnt(6)
	v_pk_fma_f32 v[44:45], v[42:43], v[60:61], v[44:45] op_sel:[1,0,0] op_sel_hi:[1,1,1]
	v_pk_fma_f32 v[46:47], v[42:43], v[62:63], v[46:47] op_sel:[1,0,0] op_sel_hi:[1,1,1]
	v_pk_fma_f32 v[48:49], v[42:43], v[64:65], v[48:49] op_sel:[1,0,0] op_sel_hi:[1,1,1]
	v_pk_fma_f32 v[68:69], v[42:43], v[72:73], v[68:69] op_sel:[1,0,0] op_sel_hi:[1,1,1]
	ds_read2_b32 v[60:61], v50 offset0:47 offset1:48
	ds_read_b32 v62, v50 offset:308
	ds_read2_b32 v[64:65], v50 offset0:78 offset1:79
	ds_read2_b32 v[72:73], v50 offset0:80 offset1:81
	s_waitcnt lgkmcnt(6)
	v_fmac_f32_e32 v45, v44, v74
	v_pk_fma_f32 v[46:47], v[44:45], v[76:77], v[46:47] op_sel:[0,0,0] op_sel_hi:[0,1,1]
	v_pk_fma_f32 v[48:49], v[44:45], v[52:53], v[48:49] op_sel:[0,0,0] op_sel_hi:[0,1,1]
	v_pk_fma_f32 v[68:69], v[44:45], v[54:55], v[68:69] op_sel:[0,0,0] op_sel_hi:[0,1,1]
	ds_read2_b32 v[74:75], v50 offset0:111 offset1:112
	ds_read2_b32 v[76:77], v50 offset0:113 offset1:114
	ds_read_b32 v52, v50 offset:580
	ds_read2_b32 v[54:55], v50 offset0:146 offset1:147
	s_waitcnt lgkmcnt(6)
	v_pk_fma_f32 v[46:47], v[44:45], v[56:57], v[46:47] op_sel:[1,0,0] op_sel_hi:[1,1,1]
	v_pk_fma_f32 v[48:49], v[44:45], v[58:59], v[48:49] op_sel:[1,0,0] op_sel_hi:[1,1,1]
	v_pk_fma_f32 v[68:69], v[44:45], v[60:61], v[68:69] op_sel:[1,0,0] op_sel_hi:[1,1,1]
	v_fmac_f32_e32 v47, v46, v62
	ds_read2_b32 v[56:57], v50 offset0:179 offset1:180
	ds_read_b32 v58, v50 offset:852
	s_waitcnt lgkmcnt(4)
	v_pk_fma_f32 v[48:49], v[46:47], v[64:65], v[48:49] op_sel:[0,0,0] op_sel_hi:[0,1,1]
	v_pk_fma_f32 v[68:69], v[46:47], v[72:73], v[68:69] op_sel:[0,0,0] op_sel_hi:[0,1,1]
	v_pk_fma_f32 v[48:49], v[46:47], v[74:75], v[48:49] op_sel:[1,0,0] op_sel_hi:[1,1,1]
	v_pk_fma_f32 v[68:69], v[46:47], v[76:77], v[68:69] op_sel:[1,0,0] op_sel_hi:[1,1,1]
	s_waitcnt lgkmcnt(0)
	v_fmac_f32_e32 v49, v48, v52
	v_pk_fma_f32 v[68:69], v[48:49], v[54:55], v[68:69] op_sel:[0,0,0] op_sel_hi:[0,1,1]
	v_pk_fma_f32 v[68:69], v[48:49], v[56:57], v[68:69] op_sel:[1,0,0] op_sel_hi:[1,1,1]
	v_fmac_f32_e32 v69, v68, v58
	v_mul_u32_u24_e32 v35, 0x440, v67
	v_mul_u32_u24_e32 v50, 0x520, v67
	v_mul_u32_u24_e32 v67, 0x44, v34
	v_add_u32_e32 v35, v35, v67
	v_lshl_add_u32 v50, v34, 1, v50
	v_add_u32_e32 v35, 0x3100, v35
	v_add_u32_e32 v50, 0xe3c0, v50
	ds_write2_b32 v35, v36, v37 offset0:0 offset1:1
	ds_write2_b32 v35, v38, v39 offset0:2 offset1:3
	ds_write2_b32 v35, v40, v41 offset0:4 offset1:5
	ds_write2_b32 v35, v42, v43 offset0:6 offset1:7
	ds_write2_b32 v35, v44, v45 offset0:8 offset1:9
	ds_write2_b32 v35, v46, v47 offset0:10 offset1:11
	ds_write2_b32 v35, v48, v49 offset0:12 offset1:13
	ds_write2_b32 v35, v68, v69 offset0:14 offset1:15
	v_cvt_pk_bf16_f32 v52, v36, v37
	ds_write_b16 v50, v52 offset:0
	ds_write_b16_d16_hi v50, v52 offset:80
	v_cvt_pk_bf16_f32 v54, v38, v39
	ds_write_b16 v50, v54 offset:160
	ds_write_b16_d16_hi v50, v54 offset:240
	v_cvt_pk_bf16_f32 v56, v40, v41
	ds_write_b16 v50, v56 offset:320
	ds_write_b16_d16_hi v50, v56 offset:400
	v_cvt_pk_bf16_f32 v58, v42, v43
	ds_write_b16 v50, v58 offset:480
	ds_write_b16_d16_hi v50, v58 offset:560
	v_cvt_pk_bf16_f32 v60, v44, v45
	ds_write_b16 v50, v60 offset:640
	ds_write_b16_d16_hi v50, v60 offset:720
	v_cvt_pk_bf16_f32 v62, v46, v47
	ds_write_b16 v50, v62 offset:800
	ds_write_b16_d16_hi v50, v62 offset:880
	v_cvt_pk_bf16_f32 v64, v48, v49
	ds_write_b16 v50, v64 offset:960
	ds_write_b16_d16_hi v50, v64 offset:1040
	v_cvt_pk_bf16_f32 v72, v68, v69
	ds_write_b16 v50, v72 offset:1120
	ds_write_b16_d16_hi v50, v72 offset:1200
.LBB0_1213:
	s_or_b64 exec, exec, s[58:59]
	s_cmp_lg_u64 s[54:55], 0
	s_cbranch_scc1 .Le23_skip_b
	v_and_b32_e32 v34, 15, v141
	v_bfe_u32 v35, v141, 4, 2
	v_mul_u32_u24_e32 v36, 0x84, v35
	v_mul_u32_u24_e32 v37, 0x44, v34
	v_mul_u32_u24_e32 v38, 0x110, v35
	v_lshl_add_u32 v36, v34, 2, v36
	v_lshl_add_u32 v37, v35, 2, v37
	v_lshl_add_u32 v38, v34, 2, v38
	ds_read_b32 v40, v36 offset:8384
	ds_read_b32 v44, v37 offset:12544
	ds_read_b32 v41, v36 offset:8912
	ds_read_b32 v45, v37 offset:12560
	ds_read_b32 v42, v36 offset:9440
	ds_read_b32 v46, v37 offset:12576
	ds_read_b32 v43, v36 offset:9968
	ds_read_b32 v47, v37 offset:12592
	ds_read_b32 v214, v38 offset:13632
	ds_read_b32 v215, v38 offset:13700
	ds_read_b32 v216, v38 offset:13768
	ds_read_b32 v217, v38 offset:13836
	v_mul_u32_u24_e32 v48, 0x50, v34
	v_lshl_add_u32 v48, v35, 3, v48
	v_bfe_u32 v39, v141, 2, 4
	v_mul_u32_u24_e32 v39, 0x50, v39
	v_and_b32_e32 v34, 3, v141
	v_lshl_add_u32 v39, v34, 3, v39
	v_mov_b32_e32 v230, 0
	v_mov_b32_e32 v231, 0
	ds_write_b64 v39, v[230:231] offset:58336
	s_waitcnt lgkmcnt(11)
	v_mfma_f32_16x16x4_f32 v[220:223], v40, v44, 0
	s_waitcnt lgkmcnt(9)
	v_mfma_f32_16x16x4_f32 v[220:223], v41, v45, v[220:223]
	s_waitcnt lgkmcnt(7)
	v_mfma_f32_16x16x4_f32 v[220:223], v42, v46, v[220:223]
	s_waitcnt lgkmcnt(5)
	v_mfma_f32_16x16x4_f32 v[220:223], v43, v47, v[220:223]
	s_waitcnt lgkmcnt(1)
	s_nop 9
	v_mfma_f32_16x16x4_f32 v[224:227], v220, v214, 0
	v_mfma_f32_16x16x4_f32 v[224:227], v221, v215, v[224:227]
	v_mfma_f32_16x16x4_f32 v[224:227], v222, v216, v[224:227]
	v_mfma_f32_16x16x4_f32 v[224:227], v223, v217, v[224:227]
	s_nop 9
	v_cvt_pk_bf16_f32 v228, v224, v225
	v_cvt_pk_bf16_f32 v229, v226, v227
	ds_write_b64 v48, v[228:229] offset:59584

.LBB0_1220:
	s_and_b64 vcc, exec, s[8:9]
	s_cbranch_vccz .LBB0_1101
	s_ashr_i32 s56, s81, 3
	s_ashr_i32 s12, s81, 8
	s_and_b32 s52, s56, 15
	v_readfirstlane_b32 s54, v176
	s_cmpk_lt_u32 s54, 0x80
	s_cselect_b64 s[8:9], -1, 0
	s_cmpk_gt_u32 s54, 0x7f
	s_cselect_b64 s[48:49], -1, 0
	s_bfe_u32 s55, s54, 0x10006
	s_and_b64 s[10:11], s[8:9], exec
	s_cselect_b32 s10, 0xf800000, s66
	s_add_u32 s40, s14, s10
	s_addc_u32 s50, s15, 0
	s_ashr_i32 s13, s12, 31
	s_lshl_b64 s[10:11], s[12:13], 17
	s_add_u32 s10, s40, s10
	s_addc_u32 s11, s50, s11
	s_lshl_b32 s82, s55, 5
	s_lshl_b32 s40, s52, 6
	v_or_b32_e32 v0, s82, v135
	v_or_b32_e32 v0, s40, v0
	v_lshlrev_b32_e32 v0, 7, v0
	v_lshl_add_u64 v[2:3], s[10:11], 0, v[0:1]
	s_and_b64 s[10:11], s[8:9], exec
	s_cselect_b32 s10, 0xa0, s67
	v_mov_b32_e32 v141, v1
	s_add_u32 s10, s0, s10
	v_lshl_add_u64 v[2:3], v[2:3], 0, v[140:141]
	s_addc_u32 s11, s1, 0
	global_load_dwordx4 v[82:85], v[2:3], off
	global_load_dwordx4 v[86:89], v[2:3], off offset:32
	global_load_dwordx4 v[90:93], v[2:3], off offset:64
	global_load_dwordx4 v[94:97], v[2:3], off offset:96
	s_load_dwordx2 s[10:11], s[10:11], 0x0
	s_lshl_b32 s13, s12, 10
	s_or_b32 s13, s40, s13
	s_or_b32 s13, s82, s13
	v_or_b32_e32 v2, s13, v135
	v_ashrrev_i32_e32 v3, 31, v2
	s_waitcnt lgkmcnt(0)
	v_lshl_add_u64 v[2:3], v[2:3], 2, s[10:11]
	global_load_dword v157, v[2:3], off
	s_and_saveexec_b64 s[10:11], s[6:7]
	s_cbranch_execz .LBB0_1223
	v_or_b32_e32 v0, s40, v176
	v_lshlrev_b32_e32 v0, 2, v0
	global_load_dword v2, v0, s[16:17]
	global_load_dword v3, v0, s[18:19]
	s_nop 0
	global_load_dword v0, v0, s[28:29]
	s_waitcnt vmcnt(1)
	ds_write2st64_b32 v151, v2, v3 offset0:238 offset1:239
	s_waitcnt vmcnt(0)
	ds_write_b32 v137, v0 offset:61632

.LBB0_1234:
	s_lshl_b32 s83, s53, 12
	s_bitset1_b32 s83, 13
	s_lshl_b32 s91, s10, 9
	s_and_b64 s[10:11], s[8:9], exec
	s_cselect_b32 s50, 0xe200000, s68
	s_lshl_b32 s10, s12, 6
	s_ashr_i32 s11, s10, 31
	s_add_u32 s12, s14, s50
	s_addc_u32 s51, s15, 0
	s_lshl_b64 s[10:11], s[10:11], 1
	s_add_u32 s50, s12, s10
	s_addc_u32 s51, s51, s11
	s_xor_b32 s12, s91, 0xfe0
	s_cmpk_lt_u32 s81, 0x100
	s_cselect_b64 s[10:11], -1, 0
	s_and_b64 s[56:57], s[10:11], exec
	s_cselect_b32 s12, s91, s12
	v_cndmask_b32_e64 v0, v149, v135, s[10:11]
	s_or_b32 s12, s83, s12
	v_or_b32_e32 v0, s12, v0
	v_lshlrev_b32_e32 v0, 8, v0
	v_lshl_add_u64 v[34:35], s[50:51], 0, v[0:1]
	v_mov_b32_e32 v141, v1
	v_cndmask_b32_e64 v0, v150, v148, s[10:11]
	v_lshl_add_u64 v[34:35], v[34:35], 0, v[140:141]
	v_add_u32_e32 v0, s12, v0
	v_or_b32_e32 v38, s40, v147
	global_load_dwordx4 v[110:113], v[34:35], off offset:96
	global_load_dwordx4 v[106:109], v[34:35], off offset:64
	global_load_dwordx4 v[102:105], v[34:35], off offset:32
	global_load_dwordx4 v[98:101], v[34:35], off
	v_lshlrev_b64 v[34:35], 11, v[0:1]
	v_lshl_add_u64 v[36:37], s[36:37], 0, v[34:35]
	v_lshlrev_b32_e32 v38, 1, v38
	v_mov_b32_e32 v39, v1
	v_lshl_add_u64 v[40:41], s[34:35], 0, v[34:35]
	v_lshl_add_u64 v[34:35], s[30:31], 0, v[34:35]
	v_lshl_add_u64 v[36:37], v[36:37], 0, v[38:39]
	v_lshl_add_u64 v[34:35], v[34:35], 0, v[38:39]
	v_lshl_add_u64 v[40:41], v[40:41], 0, v[38:39]
	global_load_dwordx4 v[118:121], v[36:37], off
	global_load_dwordx4 v[114:117], v[40:41], off
	global_load_dwordx4 v[122:125], v[34:35], off
	s_lshl_b32 s12, s52, 2
	s_add_u32 s52, s64, s12
	s_addc_u32 s53, s65, 0
	s_and_b64 s[56:57], s[8:9], exec
	s_cmp_eq_u32 s13, 1
	s_cselect_b32 s85, s69, 0x5300
	s_cmp_eq_u32 s13, 2
	s_cselect_b32 s85, s69, s85
	s_cmp_eq_u32 s55, 0
	s_cselect_b32 s86, s70, 0x7700
	s_cmp_eq_u32 s13, 0
	s_cselect_b32 s12, s71, 0xd9c0
	s_cmp_lg_u32 s13, 1
	s_cselect_b32 s87, s12, 0xc5c0
	s_cmp_lg_u32 s13, 2
	s_cselect_b64 s[54:55], -1, 0
	s_lshl_b32 s12, s40, 2
	s_add_u32 s56, s62, s12
	s_mov_b32 s84, 0
	s_addc_u32 s57, s63, 0
	s_lshl_b32 s88, s82, 1
	s_xor_b32 s89, s91, 0xfc0
	v_mov_b32_e32 v142, v0
	s_branch .LBB0_1236

.LBB0_1238:
	v_or_b32_e32 v71, s82, v70
	s_mov_b64 s[12:13], -1
	s_andn2_b64 vcc, exec, s[8:9]
	s_nop 7
	v_add_f32_e32 v58, v157, v34
	v_mul_u32_u24_e32 v34, 0x410, v51
	v_add_f32_e32 v57, v157, v35
	v_add_f32_e32 v56, v157, v36
	v_add_f32_e32 v55, v157, v37
	v_add_f32_e32 v54, v157, v38
	v_add_f32_e32 v53, v157, v39
	v_add_f32_e32 v52, v157, v40
	v_add_f32_e32 v50, v157, v41
	v_add_f32_e32 v42, v157, v42
	v_add_f32_e32 v41, v157, v43
	v_add_f32_e32 v40, v157, v44
	v_add_f32_e32 v39, v157, v45
	v_add_f32_e32 v38, v157, v46
	v_add_f32_e32 v37, v157, v47
	v_add_f32_e32 v36, v157, v48
	v_add_f32_e32 v35, v157, v49
	s_cbranch_vccnz .LBB0_1240
	v_mul_f32_e32 v43, 0xbfb8aa3b, v58
	v_mul_f32_e32 v45, 0xbfb8aa3b, v57
	v_exp_f32_e32 v44, v43
	v_exp_f32_e32 v45, v45
	v_mul_f32_e32 v48, 0xbfb8aa3b, v56
	v_mul_f32_e32 v49, 0xbfb8aa3b, v55
	v_add_f32_e32 v44, 1.0, v44
	v_add_f32_e32 v45, 1.0, v45
	v_rcp_f32_e32 v44, v44
	v_rcp_f32_e32 v45, v45
	v_exp_f32_e32 v48, v48
	v_exp_f32_e32 v49, v49
	v_mul_u32_u24_e32 v43, 0x410, v51
	v_lshl_add_u32 v46, v71, 2, v43
	v_add_u32_e32 v47, 0x2000, v46
	ds_write2_b32 v47, v44, v45 offset0:32 offset1:97
	v_add_f32_e32 v44, 1.0, v48
	v_add_f32_e32 v45, 1.0, v49
	v_mul_f32_e32 v48, 0xbfb8aa3b, v54
	v_mul_f32_e32 v49, 0xbfb8aa3b, v53
	v_rcp_f32_e32 v44, v44
	v_rcp_f32_e32 v45, v45
	v_exp_f32_e32 v48, v48
	v_exp_f32_e32 v49, v49
	s_mov_b64 s[12:13], 0
	ds_write2_b32 v47, v44, v45 offset0:162 offset1:227
	v_add_f32_e32 v44, 1.0, v48
	v_add_f32_e32 v45, 1.0, v49
	v_mul_f32_e32 v48, 0xbfb8aa3b, v52
	v_mul_f32_e32 v49, 0xbfb8aa3b, v50
	v_rcp_f32_e32 v44, v44
	v_rcp_f32_e32 v45, v45
	v_exp_f32_e32 v48, v48
	v_exp_f32_e32 v49, v49
	v_add_u32_e32 v47, 0x2800, v46
	ds_write2_b32 v47, v44, v45 offset0:40 offset1:105
	v_add_f32_e32 v44, 1.0, v48
	v_add_f32_e32 v45, 1.0, v49
	v_mul_f32_e32 v48, 0xbfb8aa3b, v42
	v_mul_f32_e32 v49, 0xbfb8aa3b, v41
	v_rcp_f32_e32 v44, v44
	v_rcp_f32_e32 v45, v45
	v_exp_f32_e32 v48, v48
	v_exp_f32_e32 v49, v49
	ds_write2_b32 v47, v44, v45 offset0:170 offset1:235
	v_add_f32_e32 v44, 1.0, v48
	v_add_f32_e32 v45, 1.0, v49
	v_mul_f32_e32 v48, 0xbfb8aa3b, v40
	v_mul_f32_e32 v49, 0xbfb8aa3b, v39
	v_rcp_f32_e32 v44, v44
	v_rcp_f32_e32 v45, v45
	v_exp_f32_e32 v48, v48
	v_exp_f32_e32 v49, v49
	v_add_u32_e32 v47, 0x3000, v46
	ds_write2_b32 v47, v44, v45 offset0:48 offset1:113
	v_add_f32_e32 v44, 1.0, v48
	v_add_f32_e32 v45, 1.0, v49
	v_mul_f32_e32 v48, 0xbfb8aa3b, v38
	v_rcp_f32_e32 v44, v44
	v_rcp_f32_e32 v45, v45
	v_exp_f32_e32 v48, v48
	v_mul_f32_e32 v49, 0xbfb8aa3b, v37
	v_exp_f32_e32 v49, v49
	ds_write2_b32 v47, v44, v45 offset0:178 offset1:243
	v_add_f32_e32 v44, 1.0, v48
	v_rcp_f32_e32 v45, v44
	v_add_f32_e32 v44, 1.0, v49
	v_rcp_f32_e32 v47, v44
	v_mul_f32_e32 v44, 0xbfb8aa3b, v36
	v_exp_f32_e32 v44, v44
	v_mul_f32_e32 v48, 0xbfb8aa3b, v35
	v_exp_f32_e32 v48, v48
	v_add_u32_e32 v49, 0x3800, v46
	v_add_f32_e32 v44, 1.0, v44
	v_rcp_f32_e32 v59, v44
	v_add_f32_e32 v44, 1.0, v48
	v_rcp_f32_e32 v44, v44
	ds_write2_b32 v49, v45, v47 offset0:56 offset1:121
	ds_write_b32 v46, v59 offset:15080

.LBB0_1278:
	v_mul_u32_u24_e32 v34, 0x48, v70
	v_lshlrev_b32_e32 v66, 1, v34
	s_waitcnt lgkmcnt(0)
	s_barrier
	v_add3_u32 v50, s85, v66, v0
	ds_read_b128 v[34:37], v50
	v_add3_u32 v0, s86, v66, v0
	ds_read_b128 v[38:41], v0
	ds_read_b128 v[52:55], v50 offset:32
	ds_read_b128 v[56:59], v0 offset:32
	s_mov_b64 s[58:59], -1
	s_and_b64 vcc, exec, s[54:55]
	s_waitcnt lgkmcnt(2)
	v_mfma_f32_32x32x16_bf16 v[34:49], v[34:37], v[38:41], 0
	s_waitcnt lgkmcnt(0)
	v_mfma_f32_32x32x16_bf16 v[34:49], v[52:55], v[56:59], v[34:49]
	ds_read_b128 v[52:55], v50 offset:64
	ds_read_b128 v[56:59], v0 offset:64
	ds_read_b128 v[60:63], v50 offset:96
	ds_read_b128 v[72:75], v0 offset:96
	v_lshlrev_b32_e32 v0, 2, v51
	v_cmp_lt_u32_e64 s[12:13], v70, v0
	v_lshl_add_u32 v50, v70, 1, s87
	s_waitcnt lgkmcnt(2)
	v_mfma_f32_32x32x16_bf16 v[34:49], v[52:55], v[56:59], v[34:49]
	v_cndmask_b32_e64 v52, 0, 1, s[12:13]
	v_cmp_le_u32_e64 s[12:13], v70, v0
	s_nop 1
	v_cndmask_b32_e64 v53, 0, 1, s[12:13]
	v_cndmask_b32_e64 v52, v53, v52, s[8:9]
	v_and_b32_e32 v52, 1, v52
	s_waitcnt lgkmcnt(0)
	v_mfma_f32_32x32x16_bf16 v[34:49], v[60:63], v[72:75], v[34:49]
	v_or_b32_e32 v143, 1, v0
	v_or_b32_e32 v158, 2, v0
	v_or_b32_e32 v159, 3, v0
	v_or_b32_e32 v160, 8, v0
	v_or_b32_e32 v161, 9, v0
	v_or_b32_e32 v162, 10, v0
	v_or_b32_e32 v163, 11, v0
	v_or_b32_e32 v164, 16, v0
	v_or_b32_e32 v165, 17, v0
	v_or_b32_e32 v166, 18, v0
	v_or_b32_e32 v167, 19, v0
	v_or_b32_e32 v168, 24, v0
	v_or_b32_e32 v169, 25, v0
	v_or_b32_e32 v170, 26, v0
	v_or_b32_e32 v171, 27, v0
	s_cmp_eq_u64 s[54:55], 0
	s_cbranch_scc1 .Ld_w0_c
	s_cmp_lg_u32 s85, s69
	s_cbranch_scc1 .Ld_w23_c
	v_mul_u32_u24_e32 v52, 0x50, v0
	v_add_u32_e32 v52, v52, v50
	v_cmp_lt_u32_e32 vcc, v70, v0
	v_cmp_lt_u32_e64 s[12:13], v70, v143
	v_cmp_lt_u32_e64 s[58:59], v70, v158
	v_cndmask_b32_e64 v34, 0, v34, vcc
	v_cmp_lt_u32_e32 vcc, v70, v159
	v_cndmask_b32_e64 v35, 0, v35, s[12:13]
	v_cmp_lt_u32_e64 s[12:13], v70, v160
	v_cvt_pk_bf16_f32 v53, v34, v35
	ds_write_b16 v52, v53 offset:0
	ds_write_b16_d16_hi v52, v53 offset:80
	v_cndmask_b32_e64 v36, 0, v36, s[58:59]
	v_cmp_lt_u32_e64 s[58:59], v70, v161
	v_cndmask_b32_e64 v37, 0, v37, vcc
	v_cmp_lt_u32_e32 vcc, v70, v162
	v_cvt_pk_bf16_f32 v53, v36, v37
	ds_write_b16 v52, v53 offset:160
	ds_write_b16_d16_hi v52, v53 offset:240
	v_cndmask_b32_e64 v38, 0, v38, s[12:13]
	v_cmp_lt_u32_e64 s[12:13], v70, v163
	v_cndmask_b32_e64 v39, 0, v39, s[58:59]
	v_cmp_lt_u32_e64 s[58:59], v70, v164
	v_cvt_pk_bf16_f32 v53, v38, v39
	ds_write_b16 v52, v53 offset:640
	ds_write_b16_d16_hi v52, v53 offset:720
	v_cndmask_b32_e64 v40, 0, v40, vcc
	v_cmp_lt_u32_e32 vcc, v70, v165
	v_cndmask_b32_e64 v41, 0, v41, s[12:13]
	v_cmp_lt_u32_e64 s[12:13], v70, v166
	v_cvt_pk_bf16_f32 v53, v40, v41
	ds_write_b16 v52, v53 offset:800
	ds_write_b16_d16_hi v52, v53 offset:880
	v_cndmask_b32_e64 v42, 0, v42, s[58:59]
	v_cmp_lt_u32_e64 s[58:59], v70, v167
	v_cndmask_b32_e64 v43, 0, v43, vcc
	v_cmp_lt_u32_e32 vcc, v70, v168
	v_cvt_pk_bf16_f32 v53, v42, v43
	ds_write_b16 v52, v53 offset:1280
	ds_write_b16_d16_hi v52, v53 offset:1360
	v_cndmask_b32_e64 v44, 0, v44, s[12:13]
	v_cmp_lt_u32_e64 s[12:13], v70, v169
	v_cndmask_b32_e64 v45, 0, v45, s[58:59]
	v_cmp_lt_u32_e64 s[58:59], v70, v170
	v_cvt_pk_bf16_f32 v53, v44, v45
	ds_write_b16 v52, v53 offset:1440
	ds_write_b16_d16_hi v52, v53 offset:1520
	v_cndmask_b32_e64 v46, 0, v46, vcc
	v_cmp_lt_u32_e32 vcc, v70, v171
	v_cndmask_b32_e64 v47, 0, v47, s[12:13]
	v_cvt_pk_bf16_f32 v53, v46, v47
	ds_write_b16 v52, v53 offset:1920
	ds_write_b16_d16_hi v52, v53 offset:2000
	v_cndmask_b32_e64 v48, 0, v48, s[58:59]
	v_cndmask_b32_e64 v49, 0, v49, vcc
	v_cvt_pk_bf16_f32 v53, v48, v49
	ds_write_b16 v52, v53 offset:2080
	ds_write_b16_d16_hi v52, v53 offset:2160
	s_branch .Ld_done_c
